# S3 global without fences + XCD-local S4-S6 + 15us XCD-group stagger at P4
# baseline (speedup 1.0000x reference)
.LBB0_672:
	s_or_b64 exec, exec, s[8:9]
	s_waitcnt vmcnt(0)
	s_cmp_lg_u32 s99, 0
	s_cbranch_scc1 .Ls3nf_0
	buffer_inv sc1

.LBB0_673:
	s_andn2_saveexec_b64 s[6:7], s[6:7]
	s_cbranch_execz .LBB0_693
	s_mov_b64 s[6:7], exec
	s_cmp_lg_u32 s99, 0
	s_cbranch_scc1 .Ls3nf_1
	buffer_wbl2 sc1
.Ls3nf_1:
	s_waitcnt lgkmcnt(0)
	s_waitcnt vmcnt(0)
	v_mbcnt_lo_u32_b32 v1, s6, 0
	v_mbcnt_hi_u32_b32 v1, s7, v1
	v_cmp_eq_u32_e32 vcc, 0, v1
	s_and_saveexec_b64 s[8:9], vcc
	s_cbranch_execz .LBB0_676
	s_bcnt1_i32_b64 s6, s[6:7]
	v_mov_b32_e32 v2, 0xb000
	v_mov_b32_e32 v3, s6
	global_atomic_add v2, v2, v3, s[76:77] offset:1024 sc0

.LBB0_690:
	s_or_b64 exec, exec, s[6:7]
	s_mov_b64 s[6:7], exec
	v_mbcnt_lo_u32_b32 v0, s6, 0
	v_mbcnt_hi_u32_b32 v0, s7, v0
	v_cmp_eq_u32_e32 vcc, 0, v0
	s_waitcnt vmcnt(0)
	s_cmp_lg_u32 s99, 0
	s_cbranch_scc1 .Ls3nf_2
	buffer_inv sc1
.Ls3nf_2:
	s_and_saveexec_b64 s[8:9], vcc
	s_cbranch_execz .LBB0_692
	s_bcnt1_i32_b64 s6, s[6:7]
	v_mov_b32_e32 v0, 0x2000
	v_mov_b32_e32 v1, s6
	global_atomic_add v0, v1, s[4:5] offset:1024

.LBB0_694:
	s_bitcmp1_b32 s2, 2
	s_cbranch_scc0 .Lstag4_done
	s_sleep 127
	s_sleep 127
	s_sleep 127
	s_sleep 127
